# grid barrier step 2: all waiters poll the top arrival counter against (gen+1)*nXCD, last leader skips the generation bump
# baseline (speedup 1.0000x reference)
; __device__ __forceinline__ unsigned xb_ld(unsigned* p)              { return __hip_atomic_load(p, __ATOMIC_RELAXED, __HIP_MEMORY_SCOPE_AGENT); }
; __device__ __forceinline__ unsigned xb_add(unsigned* p, unsigned v) { return __hip_atomic_fetch_add(p, v, __ATOMIC_RELAXED, __HIP_MEMORY_SCOPE_AGENT); }
; #define XB_SPIN(cond, bar) do { unsigned _sp = 0; while (cond) { \
;     if ((++_sp & 255u) == 0u) { if (xb_ld(&(bar)[XB_TMO])) break; if (_sp > XB_SPIN_CAP) { atomicAdd(&(bar)[XB_TMO], 1u); break; } } } } while (0)
; __device__ __forceinline__ void xcd_barrier(unsigned* barw, volatile LAS unsigned* stw, const int wv) {
;     ...
;         const unsigned old = xb_add(&bar[XB_XSUB(b.x)], 1u);
;         const unsigned gen = old / nloc;
;         if (old + 1u == (gen + 1u) * nloc) {
;             __builtin_amdgcn_fence(__ATOMIC_RELEASE, "agent");
;             asm volatile("s_waitcnt vmcnt(0)" ::: "memory");
;             const unsigned og = xb_add(&bar[XB_TOP], 1u);
;             const unsigned tg = og / nx;
;             if (og + 1u == (tg + 1u) * nx) xb_add(&bar[XB_TOPGEN], 1u);
;             else XB_SPIN(xb_ld(&bar[XB_TOPGEN]) == tg, bar);
;             __builtin_amdgcn_fence(__ATOMIC_ACQUIRE, "agent");
;             xb_add(&bar[XB_XGEN(b.x)], 1u);
;             asm volatile("s_waitcnt vmcnt(0)" ::: "memory");
;         } else {
;             XB_SPIN(xb_ld(&bar[XB_XGEN(b.x)]) == gen, bar);
.LBB0_113:
	s_or_b64 exec, exec, s[18:19]
	v_cvt_f32_u32_e32 v4, v2
	s_waitcnt vmcnt(0)
	v_readfirstlane_b32 s3, v3
	v_sub_u32_e32 v3, 0, v2
	v_rcp_iflag_f32_e32 v4, v4
	v_add_u32_e32 v5, s3, v1
	v_mul_f32_e32 v4, 0x4f7ffffe, v4
	v_cvt_u32_f32_e32 v4, v4
	v_mul_lo_u32 v1, v3, v4
	v_mul_hi_u32 v1, v4, v1
	v_add_u32_e32 v1, v4, v1
	v_mul_hi_u32 v1, v5, v1
	v_mul_lo_u32 v3, v1, v2
	v_sub_u32_e32 v3, v5, v3
	v_add_u32_e32 v4, 1, v1
	v_cmp_ge_u32_e32 vcc, v3, v2
	s_nop 1
	v_cndmask_b32_e32 v1, v1, v4, vcc
	v_sub_u32_e32 v4, v3, v2
	v_cndmask_b32_e32 v3, v3, v4, vcc
	v_add_u32_e32 v4, 1, v1
	v_cmp_ge_u32_e32 vcc, v3, v2
	v_add_u32_e32 v3, 1, v5
	s_nop 0
	v_cndmask_b32_e32 v1, v1, v4, vcc
	v_mul_lo_u32 v4, v2, v1
	v_add_u32_e32 v2, v4, v2
	v_cmp_ne_u32_e32 vcc, v3, v2
	s_and_saveexec_b64 s[4:5], vcc
	s_xor_b64 s[16:17], exec, s[4:5]
	s_cbranch_execz .LBB0_127
	s_waitcnt lgkmcnt(0)
	v_mad_u32_u24 v1, v1, v0, v0
	v_mov_b32_e32 v0, 0x3000
	global_load_dword v0, v0, s[12:13] offset:1024 sc1
	s_add_u32 s20, s12, 0x3400
	s_addc_u32 s21, s13, 0
	s_waitcnt vmcnt(0)
	v_cmp_lt_u32_e32 vcc, v0, v1
	s_and_saveexec_b64 s[18:19], vcc
	s_cbranch_execz .LBB0_126
	s_mov_b32 s3, 1
	s_mov_b64 s[22:23], 0
	v_mov_b32_e32 v0, 0
	s_branch .LBB0_117

; __device__ __forceinline__ unsigned xb_ld(unsigned* p)              { return __hip_atomic_load(p, __ATOMIC_RELAXED, __HIP_MEMORY_SCOPE_AGENT); }
; #define XB_SPIN(cond, bar) do { unsigned _sp = 0; while (cond) { \
;     if ((++_sp & 255u) == 0u) { if (xb_ld(&(bar)[XB_TMO])) break; if (_sp > XB_SPIN_CAP) { atomicAdd(&(bar)[XB_TMO], 1u); break; } } } } while (0)
; __device__ __forceinline__ void xcd_barrier(unsigned* barw, volatile LAS unsigned* stw, const int wv) {
;     ...
;             XB_SPIN(xb_ld(&bar[XB_XGEN(b.x)]) == gen, bar);
.LBB0_121:
	global_load_dword v2, v0, s[20:21] sc1
	s_add_i32 s3, s3, 1
	s_mov_b64 s[28:29], -1
	s_waitcnt vmcnt(0)
	v_cmp_ge_u32_e32 vcc, v2, v1
	s_orn2_b64 s[26:27], vcc, exec
	s_branch .LBB0_116

; __device__ __forceinline__ unsigned xb_ld(unsigned* p)              { return __hip_atomic_load(p, __ATOMIC_RELAXED, __HIP_MEMORY_SCOPE_AGENT); }
; __device__ __forceinline__ unsigned xb_add(unsigned* p, unsigned v) { return __hip_atomic_fetch_add(p, v, __ATOMIC_RELAXED, __HIP_MEMORY_SCOPE_AGENT); }
; #define XB_SPIN(cond, bar) do { unsigned _sp = 0; while (cond) { \
;     if ((++_sp & 255u) == 0u) { if (xb_ld(&(bar)[XB_TMO])) break; if (_sp > XB_SPIN_CAP) { atomicAdd(&(bar)[XB_TMO], 1u); break; } } } } while (0)
; __device__ __forceinline__ void xcd_barrier(unsigned* barw, volatile LAS unsigned* stw, const int wv) {
;     ...
;             const unsigned og = xb_add(&bar[XB_TOP], 1u);
;             const unsigned tg = og / nx;
;             if (og + 1u == (tg + 1u) * nx) xb_add(&bar[XB_TOPGEN], 1u);
;             else XB_SPIN(xb_ld(&bar[XB_TOPGEN]) == tg, bar);
.LBB0_130:
	s_or_b64 exec, exec, s[18:19]
	v_cvt_f32_u32_e32 v3, v0
	s_waitcnt vmcnt(0)
	v_readfirstlane_b32 s3, v2
	s_add_u32 s12, s12, 0x3400
	s_addc_u32 s13, s13, 0
	v_rcp_iflag_f32_e32 v3, v3
	v_add_u32_e32 v1, s3, v1
	s_mov_b64 s[18:19], 0
	v_mul_f32_e32 v2, 0x4f7ffffe, v3
	v_cvt_u32_f32_e32 v2, v2
	v_sub_u32_e32 v3, 0, v0
	v_mul_lo_u32 v3, v3, v2
	v_mul_hi_u32 v3, v2, v3
	v_add_u32_e32 v2, v2, v3
	v_mul_hi_u32 v2, v1, v2
	v_mul_lo_u32 v3, v2, v0
	v_sub_u32_e32 v3, v1, v3
	v_add_u32_e32 v4, 1, v2
	v_cmp_ge_u32_e32 vcc, v3, v0
	v_add_u32_e32 v1, 1, v1
	s_nop 0
	v_cndmask_b32_e32 v2, v2, v4, vcc
	v_sub_u32_e32 v4, v3, v0
	v_cndmask_b32_e32 v3, v3, v4, vcc
	v_add_u32_e32 v4, 1, v2
	v_cmp_ge_u32_e32 vcc, v3, v0
	s_nop 1
	v_cndmask_b32_e32 v2, v2, v4, vcc
	v_mul_lo_u32 v3, v0, v2
	v_add_u32_e32 v0, v3, v0
	v_mov_b32_e32 v17, v0
	v_cmp_ne_u32_e32 vcc, v1, v0
	v_mov_b64_e32 v[0:1], s[12:13]
	s_and_saveexec_b64 s[16:17], vcc
	s_cbranch_execz .LBB0_142
	v_mov_b32_e32 v0, 0
	global_load_dword v1, v0, s[12:13] sc1
	s_mov_b64 s[20:21], 0
	s_waitcnt vmcnt(0)
	v_cmp_lt_u32_e32 vcc, v1, v17
	s_and_saveexec_b64 s[18:19], vcc
	s_cbranch_execz .LBB0_141
	s_mov_b32 s3, 1
	s_branch .LBB0_134

; __device__ __forceinline__ unsigned xb_ld(unsigned* p)              { return __hip_atomic_load(p, __ATOMIC_RELAXED, __HIP_MEMORY_SCOPE_AGENT); }
; #define XB_SPIN(cond, bar) do { unsigned _sp = 0; while (cond) { \
;     if ((++_sp & 255u) == 0u) { if (xb_ld(&(bar)[XB_TMO])) break; if (_sp > XB_SPIN_CAP) { atomicAdd(&(bar)[XB_TMO], 1u); break; } } } } while (0)
; __device__ __forceinline__ void xcd_barrier(unsigned* barw, volatile LAS unsigned* stw, const int wv) {
;     ...
;             else XB_SPIN(xb_ld(&bar[XB_TOPGEN]) == tg, bar);
.LBB0_138:
	global_load_dword v1, v0, s[12:13] sc1
	s_add_i32 s3, s3, 1
	s_mov_b64 s[24:25], -1
	s_waitcnt vmcnt(0)
	v_cmp_ge_u32_e32 vcc, v1, v17
	s_orn2_b64 s[28:29], vcc, exec
	s_branch .LBB0_133

; __device__ __forceinline__ unsigned xb_ld(unsigned* p)              { return __hip_atomic_load(p, __ATOMIC_RELAXED, __HIP_MEMORY_SCOPE_AGENT); }
; __device__ __forceinline__ unsigned xb_add(unsigned* p, unsigned v) { return __hip_atomic_fetch_add(p, v, __ATOMIC_RELAXED, __HIP_MEMORY_SCOPE_AGENT); }
; #define XB_SPIN(cond, bar) do { unsigned _sp = 0; while (cond) { \
;     if ((++_sp & 255u) == 0u) { if (xb_ld(&(bar)[XB_TMO])) break; if (_sp > XB_SPIN_CAP) { atomicAdd(&(bar)[XB_TMO], 1u); break; } } } } while (0)
; __device__ __forceinline__ void xcd_barrier(unsigned* barw, volatile LAS unsigned* stw, const int wv) {
;     ...
;         const unsigned old = xb_add(&bar[XB_XSUB(b.x)], 1u);
;         const unsigned gen = old / nloc;
;         if (old + 1u == (gen + 1u) * nloc) {
;             __builtin_amdgcn_fence(__ATOMIC_RELEASE, "agent");
;             asm volatile("s_waitcnt vmcnt(0)" ::: "memory");
;             const unsigned og = xb_add(&bar[XB_TOP], 1u);
;             const unsigned tg = og / nx;
;             if (og + 1u == (tg + 1u) * nx) xb_add(&bar[XB_TOPGEN], 1u);
;             else XB_SPIN(xb_ld(&bar[XB_TOPGEN]) == tg, bar);
;             __builtin_amdgcn_fence(__ATOMIC_ACQUIRE, "agent");
;             xb_add(&bar[XB_XGEN(b.x)], 1u);
;             asm volatile("s_waitcnt vmcnt(0)" ::: "memory");
;         } else {
;             XB_SPIN(xb_ld(&bar[XB_XGEN(b.x)]) == gen, bar);
.LBB0_181:
	s_or_b64 exec, exec, s[18:19]
	v_cvt_f32_u32_e32 v4, v2
	s_waitcnt vmcnt(0)
	v_readfirstlane_b32 s4, v3
	v_sub_u32_e32 v3, 0, v2
	v_rcp_iflag_f32_e32 v4, v4
	v_add_u32_e32 v5, s4, v1
	v_mul_f32_e32 v4, 0x4f7ffffe, v4
	v_cvt_u32_f32_e32 v4, v4
	v_mul_lo_u32 v1, v3, v4
	v_mul_hi_u32 v1, v4, v1
	v_add_u32_e32 v1, v4, v1
	v_mul_hi_u32 v1, v5, v1
	v_mul_lo_u32 v3, v1, v2
	v_sub_u32_e32 v3, v5, v3
	v_add_u32_e32 v4, 1, v1
	v_cmp_ge_u32_e32 vcc, v3, v2
	s_nop 1
	v_cndmask_b32_e32 v1, v1, v4, vcc
	v_sub_u32_e32 v4, v3, v2
	v_cndmask_b32_e32 v3, v3, v4, vcc
	v_add_u32_e32 v4, 1, v1
	v_cmp_ge_u32_e32 vcc, v3, v2
	v_add_u32_e32 v3, 1, v5
	s_nop 0
	v_cndmask_b32_e32 v1, v1, v4, vcc
	v_mul_lo_u32 v4, v2, v1
	v_add_u32_e32 v2, v4, v2
	v_cmp_ne_u32_e32 vcc, v3, v2
	s_and_saveexec_b64 s[4:5], vcc
	s_xor_b64 s[16:17], exec, s[4:5]
	s_cbranch_execz .LBB0_195
	s_waitcnt lgkmcnt(0)
	v_mad_u32_u24 v1, v1, v0, v0
	v_mov_b32_e32 v0, 0x3000
	global_load_dword v0, v0, s[10:11] offset:1024 sc1
	s_add_u32 s20, s10, 0x3400
	s_addc_u32 s21, s11, 0
	s_waitcnt vmcnt(0)
	v_cmp_lt_u32_e32 vcc, v0, v1
	s_and_saveexec_b64 s[18:19], vcc
	s_cbranch_execz .LBB0_194
	s_mov_b32 s4, 1
	s_mov_b64 s[22:23], 0
	v_mov_b32_e32 v0, 0
	s_branch .LBB0_185

; __device__ __forceinline__ unsigned xb_ld(unsigned* p)              { return __hip_atomic_load(p, __ATOMIC_RELAXED, __HIP_MEMORY_SCOPE_AGENT); }
; #define XB_SPIN(cond, bar) do { unsigned _sp = 0; while (cond) { \
;     if ((++_sp & 255u) == 0u) { if (xb_ld(&(bar)[XB_TMO])) break; if (_sp > XB_SPIN_CAP) { atomicAdd(&(bar)[XB_TMO], 1u); break; } } } } while (0)
; __device__ __forceinline__ void xcd_barrier(unsigned* barw, volatile LAS unsigned* stw, const int wv) {
;     ...
;             XB_SPIN(xb_ld(&bar[XB_XGEN(b.x)]) == gen, bar);
.LBB0_189:
	global_load_dword v2, v0, s[20:21] sc1
	s_add_i32 s4, s4, 1
	s_mov_b64 s[28:29], -1
	s_waitcnt vmcnt(0)
	v_cmp_ge_u32_e32 vcc, v2, v1
	s_orn2_b64 s[26:27], vcc, exec
	s_branch .LBB0_184

; __device__ __forceinline__ unsigned xb_ld(unsigned* p)              { return __hip_atomic_load(p, __ATOMIC_RELAXED, __HIP_MEMORY_SCOPE_AGENT); }
; __device__ __forceinline__ unsigned xb_add(unsigned* p, unsigned v) { return __hip_atomic_fetch_add(p, v, __ATOMIC_RELAXED, __HIP_MEMORY_SCOPE_AGENT); }
; #define XB_SPIN(cond, bar) do { unsigned _sp = 0; while (cond) { \
;     if ((++_sp & 255u) == 0u) { if (xb_ld(&(bar)[XB_TMO])) break; if (_sp > XB_SPIN_CAP) { atomicAdd(&(bar)[XB_TMO], 1u); break; } } } } while (0)
; __device__ __forceinline__ void xcd_barrier(unsigned* barw, volatile LAS unsigned* stw, const int wv) {
;     ...
;             const unsigned og = xb_add(&bar[XB_TOP], 1u);
;             const unsigned tg = og / nx;
;             if (og + 1u == (tg + 1u) * nx) xb_add(&bar[XB_TOPGEN], 1u);
;             else XB_SPIN(xb_ld(&bar[XB_TOPGEN]) == tg, bar);
.LBB0_198:
	s_or_b64 exec, exec, s[18:19]
	v_cvt_f32_u32_e32 v3, v0
	s_waitcnt vmcnt(0)
	v_readfirstlane_b32 s4, v2
	s_add_u32 s10, s10, 0x3400
	s_addc_u32 s11, s11, 0
	v_rcp_iflag_f32_e32 v3, v3
	v_add_u32_e32 v1, s4, v1
	s_mov_b64 s[18:19], 0
	v_mul_f32_e32 v2, 0x4f7ffffe, v3
	v_cvt_u32_f32_e32 v2, v2
	v_sub_u32_e32 v3, 0, v0
	v_mul_lo_u32 v3, v3, v2
	v_mul_hi_u32 v3, v2, v3
	v_add_u32_e32 v2, v2, v3
	v_mul_hi_u32 v2, v1, v2
	v_mul_lo_u32 v3, v2, v0
	v_sub_u32_e32 v3, v1, v3
	v_add_u32_e32 v4, 1, v2
	v_cmp_ge_u32_e32 vcc, v3, v0
	v_add_u32_e32 v1, 1, v1
	s_nop 0
	v_cndmask_b32_e32 v2, v2, v4, vcc
	v_sub_u32_e32 v4, v3, v0
	v_cndmask_b32_e32 v3, v3, v4, vcc
	v_add_u32_e32 v4, 1, v2
	v_cmp_ge_u32_e32 vcc, v3, v0
	s_nop 1
	v_cndmask_b32_e32 v2, v2, v4, vcc
	v_mul_lo_u32 v3, v0, v2
	v_add_u32_e32 v0, v3, v0
	v_mov_b32_e32 v17, v0
	v_cmp_ne_u32_e32 vcc, v1, v0
	v_mov_b64_e32 v[0:1], s[10:11]
	s_and_saveexec_b64 s[16:17], vcc
	s_cbranch_execz .LBB0_210
	v_mov_b32_e32 v0, 0
	global_load_dword v1, v0, s[10:11] sc1
	s_mov_b64 s[20:21], 0
	s_waitcnt vmcnt(0)
	v_cmp_lt_u32_e32 vcc, v1, v17
	s_and_saveexec_b64 s[18:19], vcc
	s_cbranch_execz .LBB0_209
	s_mov_b32 s4, 1
	s_branch .LBB0_202

; __device__ __forceinline__ unsigned xb_ld(unsigned* p)              { return __hip_atomic_load(p, __ATOMIC_RELAXED, __HIP_MEMORY_SCOPE_AGENT); }
; #define XB_SPIN(cond, bar) do { unsigned _sp = 0; while (cond) { \
;     if ((++_sp & 255u) == 0u) { if (xb_ld(&(bar)[XB_TMO])) break; if (_sp > XB_SPIN_CAP) { atomicAdd(&(bar)[XB_TMO], 1u); break; } } } } while (0)
; __device__ __forceinline__ void xcd_barrier(unsigned* barw, volatile LAS unsigned* stw, const int wv) {
;     ...
;             else XB_SPIN(xb_ld(&bar[XB_TOPGEN]) == tg, bar);
.LBB0_206:
	global_load_dword v1, v0, s[10:11] sc1
	s_add_i32 s4, s4, 1
	s_mov_b64 s[24:25], -1
	s_waitcnt vmcnt(0)
	v_cmp_ge_u32_e32 vcc, v1, v17
	s_orn2_b64 s[28:29], vcc, exec
	s_branch .LBB0_201

; __device__ __forceinline__ unsigned xb_ld(unsigned* p)              { return __hip_atomic_load(p, __ATOMIC_RELAXED, __HIP_MEMORY_SCOPE_AGENT); }
; __device__ __forceinline__ unsigned xb_add(unsigned* p, unsigned v) { return __hip_atomic_fetch_add(p, v, __ATOMIC_RELAXED, __HIP_MEMORY_SCOPE_AGENT); }
; #define XB_SPIN(cond, bar) do { unsigned _sp = 0; while (cond) { \
;     if ((++_sp & 255u) == 0u) { if (xb_ld(&(bar)[XB_TMO])) break; if (_sp > XB_SPIN_CAP) { atomicAdd(&(bar)[XB_TMO], 1u); break; } } } } while (0)
; __device__ __forceinline__ void xcd_barrier(unsigned* barw, volatile LAS unsigned* stw, const int wv) {
;     ...
;         const unsigned old = xb_add(&bar[XB_XSUB(b.x)], 1u);
;         const unsigned gen = old / nloc;
;         if (old + 1u == (gen + 1u) * nloc) {
;             __builtin_amdgcn_fence(__ATOMIC_RELEASE, "agent");
;             asm volatile("s_waitcnt vmcnt(0)" ::: "memory");
;             const unsigned og = xb_add(&bar[XB_TOP], 1u);
;             const unsigned tg = og / nx;
;             if (og + 1u == (tg + 1u) * nx) xb_add(&bar[XB_TOPGEN], 1u);
;             else XB_SPIN(xb_ld(&bar[XB_TOPGEN]) == tg, bar);
;             __builtin_amdgcn_fence(__ATOMIC_ACQUIRE, "agent");
;             xb_add(&bar[XB_XGEN(b.x)], 1u);
;             asm volatile("s_waitcnt vmcnt(0)" ::: "memory");
;         } else {
;             XB_SPIN(xb_ld(&bar[XB_XGEN(b.x)]) == gen, bar);
.LBB0_325:
	s_or_b64 exec, exec, s[18:19]
	v_cvt_f32_u32_e32 v4, v2
	s_waitcnt vmcnt(0)
	v_readfirstlane_b32 s4, v3
	v_sub_u32_e32 v3, 0, v2
	v_rcp_iflag_f32_e32 v4, v4
	v_add_u32_e32 v5, s4, v1
	v_mul_f32_e32 v4, 0x4f7ffffe, v4
	v_cvt_u32_f32_e32 v4, v4
	v_mul_lo_u32 v1, v3, v4
	v_mul_hi_u32 v1, v4, v1
	v_add_u32_e32 v1, v4, v1
	v_mul_hi_u32 v1, v5, v1
	v_mul_lo_u32 v3, v1, v2
	v_sub_u32_e32 v3, v5, v3
	v_add_u32_e32 v4, 1, v1
	v_cmp_ge_u32_e32 vcc, v3, v2
	s_nop 1
	v_cndmask_b32_e32 v1, v1, v4, vcc
	v_sub_u32_e32 v4, v3, v2
	v_cndmask_b32_e32 v3, v3, v4, vcc
	v_add_u32_e32 v4, 1, v1
	v_cmp_ge_u32_e32 vcc, v3, v2
	v_add_u32_e32 v3, 1, v5
	s_nop 0
	v_cndmask_b32_e32 v1, v1, v4, vcc
	v_mul_lo_u32 v4, v2, v1
	v_add_u32_e32 v2, v4, v2
	v_cmp_ne_u32_e32 vcc, v3, v2
	s_and_saveexec_b64 s[4:5], vcc
	s_xor_b64 s[16:17], exec, s[4:5]
	s_cbranch_execz .LBB0_339
	s_waitcnt lgkmcnt(0)
	v_mad_u32_u24 v1, v1, v0, v0
	v_mov_b32_e32 v0, 0x3000
	global_load_dword v0, v0, s[14:15] offset:1024 sc1
	s_add_u32 s20, s14, 0x3400
	s_addc_u32 s21, s15, 0
	s_waitcnt vmcnt(0)
	v_cmp_lt_u32_e32 vcc, v0, v1
	s_and_saveexec_b64 s[18:19], vcc
	s_cbranch_execz .LBB0_338
	s_mov_b32 s4, 1
	s_mov_b64 s[22:23], 0
	v_mov_b32_e32 v0, 0
	s_branch .LBB0_329

; __device__ __forceinline__ unsigned xb_ld(unsigned* p)              { return __hip_atomic_load(p, __ATOMIC_RELAXED, __HIP_MEMORY_SCOPE_AGENT); }
; __device__ __forceinline__ unsigned xb_add(unsigned* p, unsigned v) { return __hip_atomic_fetch_add(p, v, __ATOMIC_RELAXED, __HIP_MEMORY_SCOPE_AGENT); }
; #define XB_SPIN(cond, bar) do { unsigned _sp = 0; while (cond) { \
;     if ((++_sp & 255u) == 0u) { if (xb_ld(&(bar)[XB_TMO])) break; if (_sp > XB_SPIN_CAP) { atomicAdd(&(bar)[XB_TMO], 1u); break; } } } } while (0)
; __device__ __forceinline__ void xcd_barrier(unsigned* barw, volatile LAS unsigned* stw, const int wv) {
;     ...
;             const unsigned og = xb_add(&bar[XB_TOP], 1u);
;             const unsigned tg = og / nx;
;             if (og + 1u == (tg + 1u) * nx) xb_add(&bar[XB_TOPGEN], 1u);
;             else XB_SPIN(xb_ld(&bar[XB_TOPGEN]) == tg, bar);
.LBB0_342:
	s_or_b64 exec, exec, s[18:19]
	v_cvt_f32_u32_e32 v3, v0
	s_waitcnt vmcnt(0)
	v_readfirstlane_b32 s4, v2
	s_add_u32 s14, s14, 0x3400
	s_addc_u32 s15, s15, 0
	v_rcp_iflag_f32_e32 v3, v3
	v_add_u32_e32 v1, s4, v1
	s_mov_b64 s[18:19], 0
	v_mul_f32_e32 v2, 0x4f7ffffe, v3
	v_cvt_u32_f32_e32 v2, v2
	v_sub_u32_e32 v3, 0, v0
	v_mul_lo_u32 v3, v3, v2
	v_mul_hi_u32 v3, v2, v3
	v_add_u32_e32 v2, v2, v3
	v_mul_hi_u32 v2, v1, v2
	v_mul_lo_u32 v3, v2, v0
	v_sub_u32_e32 v3, v1, v3
	v_add_u32_e32 v4, 1, v2
	v_cmp_ge_u32_e32 vcc, v3, v0
	v_add_u32_e32 v1, 1, v1
	s_nop 0
	v_cndmask_b32_e32 v2, v2, v4, vcc
	v_sub_u32_e32 v4, v3, v0
	v_cndmask_b32_e32 v3, v3, v4, vcc
	v_add_u32_e32 v4, 1, v2
	v_cmp_ge_u32_e32 vcc, v3, v0
	s_nop 1
	v_cndmask_b32_e32 v2, v2, v4, vcc
	v_mul_lo_u32 v3, v0, v2
	v_add_u32_e32 v0, v3, v0
	v_mov_b32_e32 v17, v0
	v_cmp_ne_u32_e32 vcc, v1, v0
	v_mov_b64_e32 v[0:1], s[14:15]
	s_and_saveexec_b64 s[16:17], vcc
	s_cbranch_execz .LBB0_354
	v_mov_b32_e32 v0, 0
	global_load_dword v1, v0, s[14:15] sc1
	s_mov_b64 s[20:21], 0
	s_waitcnt vmcnt(0)
	v_cmp_lt_u32_e32 vcc, v1, v17
	s_and_saveexec_b64 s[18:19], vcc
	s_cbranch_execz .LBB0_353
	s_mov_b32 s4, 1
	s_branch .LBB0_346

; __device__ __forceinline__ unsigned xb_ld(unsigned* p)              { return __hip_atomic_load(p, __ATOMIC_RELAXED, __HIP_MEMORY_SCOPE_AGENT); }
; #define XB_SPIN(cond, bar) do { unsigned _sp = 0; while (cond) { \
;     if ((++_sp & 255u) == 0u) { if (xb_ld(&(bar)[XB_TMO])) break; if (_sp > XB_SPIN_CAP) { atomicAdd(&(bar)[XB_TMO], 1u); break; } } } } while (0)
; __device__ __forceinline__ void xcd_barrier(unsigned* barw, volatile LAS unsigned* stw, const int wv) {
;     ...
;             else XB_SPIN(xb_ld(&bar[XB_TOPGEN]) == tg, bar);
.LBB0_350:
	global_load_dword v1, v0, s[14:15] sc1
	s_add_i32 s4, s4, 1
	s_mov_b64 s[24:25], -1
	s_waitcnt vmcnt(0)
	v_cmp_ge_u32_e32 vcc, v1, v17
	s_orn2_b64 s[28:29], vcc, exec
	s_branch .LBB0_345

; __device__ __forceinline__ unsigned xb_ld(unsigned* p)              { return __hip_atomic_load(p, __ATOMIC_RELAXED, __HIP_MEMORY_SCOPE_AGENT); }
; __device__ __forceinline__ unsigned xb_add(unsigned* p, unsigned v) { return __hip_atomic_fetch_add(p, v, __ATOMIC_RELAXED, __HIP_MEMORY_SCOPE_AGENT); }
; #define XB_SPIN(cond, bar) do { unsigned _sp = 0; while (cond) { \
;     if ((++_sp & 255u) == 0u) { if (xb_ld(&(bar)[XB_TMO])) break; if (_sp > XB_SPIN_CAP) { atomicAdd(&(bar)[XB_TMO], 1u); break; } } } } while (0)
; __device__ __forceinline__ void xcd_barrier(unsigned* barw, volatile LAS unsigned* stw, const int wv) {
;     ...
;         const unsigned old = xb_add(&bar[XB_XSUB(b.x)], 1u);
;         const unsigned gen = old / nloc;
;         if (old + 1u == (gen + 1u) * nloc) {
;             __builtin_amdgcn_fence(__ATOMIC_RELEASE, "agent");
;             asm volatile("s_waitcnt vmcnt(0)" ::: "memory");
;             const unsigned og = xb_add(&bar[XB_TOP], 1u);
;             const unsigned tg = og / nx;
;             if (og + 1u == (tg + 1u) * nx) xb_add(&bar[XB_TOPGEN], 1u);
;             else XB_SPIN(xb_ld(&bar[XB_TOPGEN]) == tg, bar);
;             __builtin_amdgcn_fence(__ATOMIC_ACQUIRE, "agent");
;             xb_add(&bar[XB_XGEN(b.x)], 1u);
;             asm volatile("s_waitcnt vmcnt(0)" ::: "memory");
;         } else {
;             XB_SPIN(xb_ld(&bar[XB_XGEN(b.x)]) == gen, bar);
.LBB0_481:
	s_or_b64 exec, exec, s[18:19]
	v_cvt_f32_u32_e32 v4, v2
	s_waitcnt vmcnt(0)
	v_readfirstlane_b32 s4, v3
	v_sub_u32_e32 v3, 0, v2
	v_rcp_iflag_f32_e32 v4, v4
	v_add_u32_e32 v5, s4, v1
	v_mul_f32_e32 v4, 0x4f7ffffe, v4
	v_cvt_u32_f32_e32 v4, v4
	v_mul_lo_u32 v1, v3, v4
	v_mul_hi_u32 v1, v4, v1
	v_add_u32_e32 v1, v4, v1
	v_mul_hi_u32 v1, v5, v1
	v_mul_lo_u32 v3, v1, v2
	v_sub_u32_e32 v3, v5, v3
	v_add_u32_e32 v4, 1, v1
	v_cmp_ge_u32_e32 vcc, v3, v2
	s_nop 1
	v_cndmask_b32_e32 v1, v1, v4, vcc
	v_sub_u32_e32 v4, v3, v2
	v_cndmask_b32_e32 v3, v3, v4, vcc
	v_add_u32_e32 v4, 1, v1
	v_cmp_ge_u32_e32 vcc, v3, v2
	v_add_u32_e32 v3, 1, v5
	s_nop 0
	v_cndmask_b32_e32 v1, v1, v4, vcc
	v_mul_lo_u32 v4, v2, v1
	v_add_u32_e32 v2, v4, v2
	v_cmp_ne_u32_e32 vcc, v3, v2
	s_and_saveexec_b64 s[4:5], vcc
	s_xor_b64 s[14:15], exec, s[4:5]
	s_cbranch_execz .LBB0_495
	s_waitcnt lgkmcnt(0)
	v_mad_u32_u24 v1, v1, v0, v0
	v_mov_b32_e32 v0, 0x3000
	global_load_dword v0, v0, s[16:17] offset:1024 sc1
	s_add_u32 s20, s16, 0x3400
	s_addc_u32 s21, s17, 0
	s_waitcnt vmcnt(0)
	v_cmp_lt_u32_e32 vcc, v0, v1
	s_and_saveexec_b64 s[18:19], vcc
	s_cbranch_execz .LBB0_494
	s_mov_b32 s4, 1
	s_mov_b64 s[22:23], 0
	v_mov_b32_e32 v0, 0
	s_branch .LBB0_485

; __device__ __forceinline__ unsigned xb_ld(unsigned* p)              { return __hip_atomic_load(p, __ATOMIC_RELAXED, __HIP_MEMORY_SCOPE_AGENT); }
; __device__ __forceinline__ unsigned xb_add(unsigned* p, unsigned v) { return __hip_atomic_fetch_add(p, v, __ATOMIC_RELAXED, __HIP_MEMORY_SCOPE_AGENT); }
; #define XB_SPIN(cond, bar) do { unsigned _sp = 0; while (cond) { \
;     if ((++_sp & 255u) == 0u) { if (xb_ld(&(bar)[XB_TMO])) break; if (_sp > XB_SPIN_CAP) { atomicAdd(&(bar)[XB_TMO], 1u); break; } } } } while (0)
; __device__ __forceinline__ void xcd_barrier(unsigned* barw, volatile LAS unsigned* stw, const int wv) {
;     ...
;             const unsigned og = xb_add(&bar[XB_TOP], 1u);
;             const unsigned tg = og / nx;
;             if (og + 1u == (tg + 1u) * nx) xb_add(&bar[XB_TOPGEN], 1u);
;             else XB_SPIN(xb_ld(&bar[XB_TOPGEN]) == tg, bar);
.LBB0_498:
	s_or_b64 exec, exec, s[18:19]
	v_cvt_f32_u32_e32 v3, v0
	s_waitcnt vmcnt(0)
	v_readfirstlane_b32 s4, v2
	s_add_u32 s14, s16, 0x3400
	s_addc_u32 s15, s17, 0
	v_rcp_iflag_f32_e32 v3, v3
	v_add_u32_e32 v1, s4, v1
	s_mov_b64 s[18:19], 0
	v_mul_f32_e32 v2, 0x4f7ffffe, v3
	v_cvt_u32_f32_e32 v2, v2
	v_sub_u32_e32 v3, 0, v0
	v_mul_lo_u32 v3, v3, v2
	v_mul_hi_u32 v3, v2, v3
	v_add_u32_e32 v2, v2, v3
	v_mul_hi_u32 v2, v1, v2
	v_mul_lo_u32 v3, v2, v0
	v_sub_u32_e32 v3, v1, v3
	v_add_u32_e32 v4, 1, v2
	v_cmp_ge_u32_e32 vcc, v3, v0
	v_add_u32_e32 v1, 1, v1
	s_nop 0
	v_cndmask_b32_e32 v2, v2, v4, vcc
	v_sub_u32_e32 v4, v3, v0
	v_cndmask_b32_e32 v3, v3, v4, vcc
	v_add_u32_e32 v4, 1, v2
	v_cmp_ge_u32_e32 vcc, v3, v0
	s_nop 1
	v_cndmask_b32_e32 v2, v2, v4, vcc
	v_mul_lo_u32 v3, v0, v2
	v_add_u32_e32 v0, v3, v0
	v_mov_b32_e32 v17, v0
	v_cmp_ne_u32_e32 vcc, v1, v0
	v_mov_b64_e32 v[0:1], s[14:15]
	s_and_saveexec_b64 s[16:17], vcc
	s_cbranch_execz .LBB0_510
	v_mov_b32_e32 v0, 0
	global_load_dword v1, v0, s[14:15] sc1
	s_mov_b64 s[20:21], 0
	s_waitcnt vmcnt(0)
	v_cmp_lt_u32_e32 vcc, v1, v17
	s_and_saveexec_b64 s[18:19], vcc
	s_cbranch_execz .LBB0_509
	s_mov_b32 s4, 1
	s_branch .LBB0_502

; __device__ __forceinline__ unsigned xb_ld(unsigned* p)              { return __hip_atomic_load(p, __ATOMIC_RELAXED, __HIP_MEMORY_SCOPE_AGENT); }
; __device__ __forceinline__ unsigned xb_add(unsigned* p, unsigned v) { return __hip_atomic_fetch_add(p, v, __ATOMIC_RELAXED, __HIP_MEMORY_SCOPE_AGENT); }
; #define XB_SPIN(cond, bar) do { unsigned _sp = 0; while (cond) { \
;     if ((++_sp & 255u) == 0u) { if (xb_ld(&(bar)[XB_TMO])) break; if (_sp > XB_SPIN_CAP) { atomicAdd(&(bar)[XB_TMO], 1u); break; } } } } while (0)
; __device__ __forceinline__ void xcd_barrier(unsigned* barw, volatile LAS unsigned* stw, const int wv) {
;     ...
;         const unsigned old = xb_add(&bar[XB_XSUB(b.x)], 1u);
;         const unsigned gen = old / nloc;
;         if (old + 1u == (gen + 1u) * nloc) {
;             __builtin_amdgcn_fence(__ATOMIC_RELEASE, "agent");
;             asm volatile("s_waitcnt vmcnt(0)" ::: "memory");
;             const unsigned og = xb_add(&bar[XB_TOP], 1u);
;             const unsigned tg = og / nx;
;             if (og + 1u == (tg + 1u) * nx) xb_add(&bar[XB_TOPGEN], 1u);
;             else XB_SPIN(xb_ld(&bar[XB_TOPGEN]) == tg, bar);
;             __builtin_amdgcn_fence(__ATOMIC_ACQUIRE, "agent");
;             xb_add(&bar[XB_XGEN(b.x)], 1u);
;             asm volatile("s_waitcnt vmcnt(0)" ::: "memory");
;         } else {
;             XB_SPIN(xb_ld(&bar[XB_XGEN(b.x)]) == gen, bar);
.LBB0_740:
	s_lshl_b32 s4, s4, 8
	s_add_u32 s12, s10, s4
	s_addc_u32 s13, s11, 0
	v_mov_b32_e32 v1, 0x1000
	v_mov_b32_e32 v3, 1
	global_atomic_add v3, v1, v3, s[12:13] offset:1024 sc0
	v_cvt_f32_u32_e32 v1, v2
	v_sub_u32_e32 v4, 0, v2
	v_rcp_iflag_f32_e32 v1, v1
	s_nop 0
	v_mul_f32_e32 v1, 0x4f7ffffe, v1
	v_cvt_u32_f32_e32 v1, v1
	v_mul_lo_u32 v4, v4, v1
	v_mul_hi_u32 v4, v1, v4
	v_add_u32_e32 v1, v1, v4
	s_waitcnt vmcnt(0)
	v_mul_hi_u32 v1, v3, v1
	v_mul_lo_u32 v4, v1, v2
	v_sub_u32_e32 v4, v3, v4
	v_add_u32_e32 v5, 1, v1
	v_cmp_ge_u32_e32 vcc, v4, v2
	v_add_u32_e32 v3, 1, v3
	s_nop 0
	v_cndmask_b32_e32 v1, v1, v5, vcc
	v_sub_u32_e32 v5, v4, v2
	v_cndmask_b32_e32 v4, v4, v5, vcc
	v_add_u32_e32 v5, 1, v1
	v_cmp_ge_u32_e32 vcc, v4, v2
	s_nop 1
	v_cndmask_b32_e32 v1, v1, v5, vcc
	v_mul_lo_u32 v4, v2, v1
	v_add_u32_e32 v2, v4, v2
	v_cmp_ne_u32_e32 vcc, v3, v2
	s_and_saveexec_b64 s[4:5], vcc
	s_xor_b64 s[14:15], exec, s[4:5]
	s_cbranch_execz .LBB0_753
	s_waitcnt lgkmcnt(0)
	v_mad_u32_u24 v1, v1, v0, v0
	v_mov_b32_e32 v0, 0x3000
	global_load_dword v0, v0, s[10:11] offset:1024 sc1
	s_add_u32 s18, s10, 0x3400
	s_addc_u32 s19, s11, 0
	s_waitcnt vmcnt(0)
	v_cmp_lt_u32_e32 vcc, v0, v1
	s_and_saveexec_b64 s[16:17], vcc
	s_cbranch_execz .LBB0_752
	s_mov_b32 s4, 1
	s_mov_b64 s[20:21], 0
	v_mov_b32_e32 v0, 0
	s_branch .LBB0_744

; __device__ __forceinline__ unsigned xb_ld(unsigned* p)              { return __hip_atomic_load(p, __ATOMIC_RELAXED, __HIP_MEMORY_SCOPE_AGENT); }
; #define XB_SPIN(cond, bar) do { unsigned _sp = 0; while (cond) { \
;     if ((++_sp & 255u) == 0u) { if (xb_ld(&(bar)[XB_TMO])) break; if (_sp > XB_SPIN_CAP) { atomicAdd(&(bar)[XB_TMO], 1u); break; } } } } while (0)
; __device__ __forceinline__ void xcd_barrier(unsigned* barw, volatile LAS unsigned* stw, const int wv) {
;     ...
;             XB_SPIN(xb_ld(&bar[XB_XGEN(b.x)]) == gen, bar);
.LBB0_748:
	global_load_dword v2, v0, s[18:19] sc1
	s_add_i32 s4, s4, 1
	s_mov_b64 s[26:27], -1
	s_waitcnt vmcnt(0)
	v_cmp_ge_u32_e32 vcc, v2, v1
	s_orn2_b64 s[24:25], vcc, exec
	s_branch .LBB0_743

; __device__ __forceinline__ unsigned xb_ld(unsigned* p)              { return __hip_atomic_load(p, __ATOMIC_RELAXED, __HIP_MEMORY_SCOPE_AGENT); }
; __device__ __forceinline__ unsigned xb_add(unsigned* p, unsigned v) { return __hip_atomic_fetch_add(p, v, __ATOMIC_RELAXED, __HIP_MEMORY_SCOPE_AGENT); }
; #define XB_SPIN(cond, bar) do { unsigned _sp = 0; while (cond) { \
;     if ((++_sp & 255u) == 0u) { if (xb_ld(&(bar)[XB_TMO])) break; if (_sp > XB_SPIN_CAP) { atomicAdd(&(bar)[XB_TMO], 1u); break; } } } } while (0)
; __device__ __forceinline__ void xcd_barrier(unsigned* barw, volatile LAS unsigned* stw, const int wv) {
;     ...
;             __builtin_amdgcn_fence(__ATOMIC_RELEASE, "agent");
;             asm volatile("s_waitcnt vmcnt(0)" ::: "memory");
;             const unsigned og = xb_add(&bar[XB_TOP], 1u);
;             const unsigned tg = og / nx;
;             if (og + 1u == (tg + 1u) * nx) xb_add(&bar[XB_TOPGEN], 1u);
;             else XB_SPIN(xb_ld(&bar[XB_TOPGEN]) == tg, bar);
.LBB0_753:
	s_andn2_saveexec_b64 s[4:5], s[14:15]
	s_cbranch_execz .LBB0_769
	buffer_wbl2 sc1
	s_waitcnt lgkmcnt(0)
	s_waitcnt vmcnt(0)
	v_mov_b32_e32 v1, 0x3000
	v_mov_b32_e32 v2, 1
	global_atomic_add v1, v1, v2, s[10:11] offset:1024 sc0
	v_cvt_f32_u32_e32 v2, v0
	v_sub_u32_e32 v3, 0, v0
	s_add_u32 s10, s10, 0x3400
	s_addc_u32 s11, s11, 0
	v_rcp_iflag_f32_e32 v2, v2
	s_mov_b64 s[16:17], 0
	v_mul_f32_e32 v2, 0x4f7ffffe, v2
	v_cvt_u32_f32_e32 v2, v2
	v_mul_lo_u32 v3, v3, v2
	v_mul_hi_u32 v3, v2, v3
	v_add_u32_e32 v2, v2, v3
	s_waitcnt vmcnt(0)
	v_mul_hi_u32 v2, v1, v2
	v_mul_lo_u32 v4, v2, v0
	v_add_u32_e32 v3, 1, v1
	v_sub_u32_e32 v1, v1, v4
	v_add_u32_e32 v5, 1, v2
	v_cmp_ge_u32_e32 vcc, v1, v0
	v_sub_u32_e32 v4, v1, v0
	s_nop 0
	v_cndmask_b32_e32 v2, v2, v5, vcc
	v_cndmask_b32_e32 v1, v1, v4, vcc
	v_add_u32_e32 v4, 1, v2
	v_cmp_ge_u32_e32 vcc, v1, v0
	s_nop 1
	v_cndmask_b32_e32 v2, v2, v4, vcc
	v_mul_lo_u32 v1, v0, v2
	v_add_u32_e32 v0, v1, v0
	v_mov_b32_e32 v17, v0
	v_cmp_ne_u32_e32 vcc, v3, v0
	v_mov_b64_e32 v[0:1], s[10:11]
	s_and_saveexec_b64 s[14:15], vcc
	s_cbranch_execz .LBB0_766
	v_mov_b32_e32 v0, 0
	global_load_dword v1, v0, s[10:11] sc1
	s_mov_b64 s[18:19], 0
	s_waitcnt vmcnt(0)
	v_cmp_lt_u32_e32 vcc, v1, v17
	s_and_saveexec_b64 s[16:17], vcc
	s_cbranch_execz .LBB0_765
	s_mov_b32 s4, 1
	s_branch .LBB0_758

; __device__ __forceinline__ unsigned xb_ld(unsigned* p)              { return __hip_atomic_load(p, __ATOMIC_RELAXED, __HIP_MEMORY_SCOPE_AGENT); }
; #define XB_SPIN(cond, bar) do { unsigned _sp = 0; while (cond) { \
;     if ((++_sp & 255u) == 0u) { if (xb_ld(&(bar)[XB_TMO])) break; if (_sp > XB_SPIN_CAP) { atomicAdd(&(bar)[XB_TMO], 1u); break; } } } } while (0)
; __device__ __forceinline__ void xcd_barrier(unsigned* barw, volatile LAS unsigned* stw, const int wv) {
;     ...
;             else XB_SPIN(xb_ld(&bar[XB_TOPGEN]) == tg, bar);
.LBB0_762:
	global_load_dword v1, v0, s[10:11] sc1
	s_add_i32 s4, s4, 1
	s_mov_b64 s[22:23], -1
	s_waitcnt vmcnt(0)
	v_cmp_ge_u32_e32 vcc, v1, v17
	s_orn2_b64 s[26:27], vcc, exec
	s_branch .LBB0_757

; __device__ __forceinline__ unsigned xb_ld(unsigned* p)              { return __hip_atomic_load(p, __ATOMIC_RELAXED, __HIP_MEMORY_SCOPE_AGENT); }
; __device__ __forceinline__ unsigned xb_add(unsigned* p, unsigned v) { return __hip_atomic_fetch_add(p, v, __ATOMIC_RELAXED, __HIP_MEMORY_SCOPE_AGENT); }
; #define XB_SPIN(cond, bar) do { unsigned _sp = 0; while (cond) { \
;     if ((++_sp & 255u) == 0u) { if (xb_ld(&(bar)[XB_TMO])) break; if (_sp > XB_SPIN_CAP) { atomicAdd(&(bar)[XB_TMO], 1u); break; } } } } while (0)
; __device__ __forceinline__ void xcd_barrier(unsigned* barw, volatile LAS unsigned* stw, const int wv) {
;     ...
;         const unsigned old = xb_add(&bar[XB_XSUB(b.x)], 1u);
;         const unsigned gen = old / nloc;
;         if (old + 1u == (gen + 1u) * nloc) {
;             __builtin_amdgcn_fence(__ATOMIC_RELEASE, "agent");
;             asm volatile("s_waitcnt vmcnt(0)" ::: "memory");
;             const unsigned og = xb_add(&bar[XB_TOP], 1u);
;             const unsigned tg = og / nx;
;             if (og + 1u == (tg + 1u) * nx) xb_add(&bar[XB_TOPGEN], 1u);
;             else XB_SPIN(xb_ld(&bar[XB_TOPGEN]) == tg, bar);
;             __builtin_amdgcn_fence(__ATOMIC_ACQUIRE, "agent");
;             xb_add(&bar[XB_XGEN(b.x)], 1u);
;             asm volatile("s_waitcnt vmcnt(0)" ::: "memory");
;         } else {
;             XB_SPIN(xb_ld(&bar[XB_XGEN(b.x)]) == gen, bar);
.LBB0_800:
	s_lshl_b32 s0, s4, 8
	s_mov_b32 s1, 0
	v_lshl_add_u64 v[4:5], v[2:3], 0, s[0:1]
	v_add_co_u32_e32 v10, vcc, 0x1000, v4
	v_mov_b32_e32 v7, 1
	s_nop 0
	v_addc_co_u32_e32 v11, vcc, 0, v5, vcc
	global_atomic_add v7, v[10:11], v7, off offset:1024 sc0
	v_cvt_f32_u32_e32 v9, v8
	v_sub_u32_e32 v10, 0, v8
	v_rcp_iflag_f32_e32 v9, v9
	s_nop 0
	v_mul_f32_e32 v9, 0x4f7ffffe, v9
	v_cvt_u32_f32_e32 v9, v9
	v_mul_lo_u32 v10, v10, v9
	v_mul_hi_u32 v10, v9, v10
	v_add_u32_e32 v9, v9, v10
	s_waitcnt vmcnt(0)
	v_mul_hi_u32 v9, v7, v9
	v_mul_lo_u32 v11, v9, v8
	v_add_u32_e32 v10, 1, v7
	v_sub_u32_e32 v7, v7, v11
	v_add_u32_e32 v12, 1, v9
	v_cmp_ge_u32_e32 vcc, v7, v8
	v_sub_u32_e32 v11, v7, v8
	s_nop 0
	v_cndmask_b32_e32 v9, v9, v12, vcc
	v_cndmask_b32_e32 v7, v7, v11, vcc
	v_add_u32_e32 v11, 1, v9
	v_cmp_ge_u32_e32 vcc, v7, v8
	s_nop 1
	v_cndmask_b32_e32 v7, v9, v11, vcc
	v_mad_u64_u32 v[8:9], s[0:1], v8, v7, v[8:9]
	v_cmp_ne_u32_e32 vcc, v10, v8
	s_and_saveexec_b64 s[0:1], vcc
	s_xor_b64 s[0:1], exec, s[0:1]
	s_cbranch_execz .LBB0_813
	v_add_co_u32_e32 v2, vcc, 0x3400, v2
	s_nop 1
	v_addc_co_u32_e32 v3, vcc, 0, v3, vcc
	global_load_dword v4, v[2:3], off sc1
	s_waitcnt lgkmcnt(0)
	v_mad_u32_u24 v7, v7, v6, v6
	s_waitcnt vmcnt(0)
	v_cmp_lt_u32_e32 vcc, v4, v7
	s_and_saveexec_b64 s[8:9], vcc
	s_cbranch_execz .LBB0_812
	s_mov_b32 s4, 1
	s_mov_b64 s[10:11], 0
	s_branch .LBB0_804

; __device__ __forceinline__ unsigned xb_ld(unsigned* p)              { return __hip_atomic_load(p, __ATOMIC_RELAXED, __HIP_MEMORY_SCOPE_AGENT); }
; #define XB_SPIN(cond, bar) do { unsigned _sp = 0; while (cond) { \
;     if ((++_sp & 255u) == 0u) { if (xb_ld(&(bar)[XB_TMO])) break; if (_sp > XB_SPIN_CAP) { atomicAdd(&(bar)[XB_TMO], 1u); break; } } } } while (0)
; __device__ __forceinline__ void xcd_barrier(unsigned* barw, volatile LAS unsigned* stw, const int wv) {
;     ...
;             XB_SPIN(xb_ld(&bar[XB_XGEN(b.x)]) == gen, bar);
.LBB0_808:
	s_andn2_b64 s[6:7], s[14:15], exec
	s_and_b64 s[14:15], s[20:21], exec
	s_or_b64 s[14:15], s[6:7], s[14:15]
	s_and_saveexec_b64 s[20:21], s[18:19]
	s_cbranch_execz .LBB0_803
	global_load_dword v4, v[2:3], off sc1
	s_add_i32 s4, s4, 1
	s_or_b64 s[14:15], s[14:15], exec
	s_waitcnt vmcnt(0)
	v_cmp_ge_u32_e32 vcc, v4, v7
	s_orn2_b64 s[16:17], vcc, exec
	s_branch .LBB0_803

; __device__ __forceinline__ unsigned xb_ld(unsigned* p)              { return __hip_atomic_load(p, __ATOMIC_RELAXED, __HIP_MEMORY_SCOPE_AGENT); }
; __device__ __forceinline__ unsigned xb_add(unsigned* p, unsigned v) { return __hip_atomic_fetch_add(p, v, __ATOMIC_RELAXED, __HIP_MEMORY_SCOPE_AGENT); }
; #define XB_SPIN(cond, bar) do { unsigned _sp = 0; while (cond) { \
;     if ((++_sp & 255u) == 0u) { if (xb_ld(&(bar)[XB_TMO])) break; if (_sp > XB_SPIN_CAP) { atomicAdd(&(bar)[XB_TMO], 1u); break; } } } } while (0)
; __device__ __forceinline__ void xcd_barrier(unsigned* barw, volatile LAS unsigned* stw, const int wv) {
;     ...
;             __builtin_amdgcn_fence(__ATOMIC_RELEASE, "agent");
;             asm volatile("s_waitcnt vmcnt(0)" ::: "memory");
;             const unsigned og = xb_add(&bar[XB_TOP], 1u);
;             const unsigned tg = og / nx;
;             if (og + 1u == (tg + 1u) * nx) xb_add(&bar[XB_TOPGEN], 1u);
;             else XB_SPIN(xb_ld(&bar[XB_TOPGEN]) == tg, bar);
.LBB0_813:
	s_andn2_saveexec_b64 s[0:1], s[0:1]
	s_cbranch_execz .LBB0_829
	v_add_co_u32_e32 v8, vcc, 0x3000, v2
	buffer_wbl2 sc1
	s_waitcnt lgkmcnt(0)
	s_waitcnt vmcnt(0)
	v_addc_co_u32_e32 v9, vcc, 0, v3, vcc
	v_mov_b32_e32 v7, 1
	global_atomic_add v7, v[8:9], v7, off offset:1024 sc0
	v_cvt_f32_u32_e32 v8, v6
	v_sub_u32_e32 v9, 0, v6
	s_mov_b64 s[0:1], 0x3400
	v_lshl_add_u64 v[2:3], v[2:3], 0, s[0:1]
	v_rcp_iflag_f32_e32 v8, v8
	s_mov_b64 s[8:9], 0
	v_mul_f32_e32 v8, 0x4f7ffffe, v8
	v_cvt_u32_f32_e32 v8, v8
	v_mul_lo_u32 v9, v9, v8
	v_mul_hi_u32 v9, v8, v9
	v_add_u32_e32 v8, v8, v9
	s_waitcnt vmcnt(0)
	v_mul_hi_u32 v8, v7, v8
	v_mul_lo_u32 v9, v8, v6
	v_add_u32_e32 v10, 1, v7
	v_sub_u32_e32 v7, v7, v9
	v_add_u32_e32 v11, 1, v8
	v_cmp_ge_u32_e32 vcc, v7, v6
	v_sub_u32_e32 v9, v7, v6
	s_nop 0
	v_cndmask_b32_e32 v8, v8, v11, vcc
	v_cndmask_b32_e32 v7, v7, v9, vcc
	v_add_u32_e32 v9, 1, v8
	v_cmp_ge_u32_e32 vcc, v7, v6
	s_nop 1
	v_cndmask_b32_e32 v7, v8, v9, vcc
	v_mad_u64_u32 v[8:9], s[0:1], v6, v7, v[6:7]
	v_cmp_ne_u32_e32 vcc, v10, v8
	s_and_saveexec_b64 s[0:1], vcc
	s_cbranch_execz .LBB0_826
	global_load_dword v6, v[2:3], off sc1
	s_mov_b64 s[10:11], 0
	s_waitcnt vmcnt(0)
	v_cmp_lt_u32_e32 vcc, v6, v8
	s_and_saveexec_b64 s[8:9], vcc
	s_cbranch_execz .LBB0_825
	s_mov_b32 s4, 1
	s_branch .LBB0_818

; __device__ __forceinline__ unsigned xb_ld(unsigned* p)              { return __hip_atomic_load(p, __ATOMIC_RELAXED, __HIP_MEMORY_SCOPE_AGENT); }
; #define XB_SPIN(cond, bar) do { unsigned _sp = 0; while (cond) { \
;     if ((++_sp & 255u) == 0u) { if (xb_ld(&(bar)[XB_TMO])) break; if (_sp > XB_SPIN_CAP) { atomicAdd(&(bar)[XB_TMO], 1u); break; } } } } while (0)
; __device__ __forceinline__ void xcd_barrier(unsigned* barw, volatile LAS unsigned* stw, const int wv) {
;     ...
;             else XB_SPIN(xb_ld(&bar[XB_TOPGEN]) == tg, bar);
.LBB0_823:
	global_load_dword v6, v[2:3], off sc1
	s_add_i32 s4, s4, 1
	s_or_b64 s[14:15], s[14:15], exec
	s_waitcnt vmcnt(0)
	v_cmp_ge_u32_e32 vcc, v6, v8
	s_orn2_b64 s[18:19], vcc, exec
	s_branch .LBB0_817

; __device__ __forceinline__ unsigned xb_ld(unsigned* p)              { return __hip_atomic_load(p, __ATOMIC_RELAXED, __HIP_MEMORY_SCOPE_AGENT); }
; __device__ __forceinline__ unsigned xb_add(unsigned* p, unsigned v) { return __hip_atomic_fetch_add(p, v, __ATOMIC_RELAXED, __HIP_MEMORY_SCOPE_AGENT); }
; #define XB_SPIN(cond, bar) do { unsigned _sp = 0; while (cond) { \
;     if ((++_sp & 255u) == 0u) { if (xb_ld(&(bar)[XB_TMO])) break; if (_sp > XB_SPIN_CAP) { atomicAdd(&(bar)[XB_TMO], 1u); break; } } } } while (0)
; __device__ __forceinline__ void xcd_barrier(unsigned* barw, volatile LAS unsigned* stw, const int wv) {
;     ...
;         const unsigned old = xb_add(&bar[XB_XSUB(b.x)], 1u);
;         const unsigned gen = old / nloc;
;         if (old + 1u == (gen + 1u) * nloc) {
;             __builtin_amdgcn_fence(__ATOMIC_RELEASE, "agent");
;             asm volatile("s_waitcnt vmcnt(0)" ::: "memory");
;             const unsigned og = xb_add(&bar[XB_TOP], 1u);
;             const unsigned tg = og / nx;
;             if (og + 1u == (tg + 1u) * nx) xb_add(&bar[XB_TOPGEN], 1u);
;             else XB_SPIN(xb_ld(&bar[XB_TOPGEN]) == tg, bar);
;             __builtin_amdgcn_fence(__ATOMIC_ACQUIRE, "agent");
;             xb_add(&bar[XB_XGEN(b.x)], 1u);
;             asm volatile("s_waitcnt vmcnt(0)" ::: "memory");
;         } else {
;             XB_SPIN(xb_ld(&bar[XB_XGEN(b.x)]) == gen, bar);
.LBB0_865:
	s_or_b64 exec, exec, s[16:17]
	v_cvt_f32_u32_e32 v4, v2
	s_waitcnt vmcnt(0)
	v_readfirstlane_b32 s4, v3
	v_sub_u32_e32 v3, 0, v2
	v_rcp_iflag_f32_e32 v4, v4
	v_add_u32_e32 v5, s4, v1
	v_mul_f32_e32 v4, 0x4f7ffffe, v4
	v_cvt_u32_f32_e32 v4, v4
	v_mul_lo_u32 v1, v3, v4
	v_mul_hi_u32 v1, v4, v1
	v_add_u32_e32 v1, v4, v1
	v_mul_hi_u32 v1, v5, v1
	v_mul_lo_u32 v3, v1, v2
	v_sub_u32_e32 v3, v5, v3
	v_add_u32_e32 v4, 1, v1
	v_cmp_ge_u32_e32 vcc, v3, v2
	s_nop 1
	v_cndmask_b32_e32 v1, v1, v4, vcc
	v_sub_u32_e32 v4, v3, v2
	v_cndmask_b32_e32 v3, v3, v4, vcc
	v_add_u32_e32 v4, 1, v1
	v_cmp_ge_u32_e32 vcc, v3, v2
	v_add_u32_e32 v3, 1, v5
	s_nop 0
	v_cndmask_b32_e32 v1, v1, v4, vcc
	v_mul_lo_u32 v4, v2, v1
	v_add_u32_e32 v2, v4, v2
	v_cmp_ne_u32_e32 vcc, v3, v2
	s_and_saveexec_b64 s[4:5], vcc
	s_xor_b64 s[14:15], exec, s[4:5]
	s_cbranch_execz .LBB0_879
	s_waitcnt lgkmcnt(0)
	v_mad_u32_u24 v1, v1, v0, v0
	v_mov_b32_e32 v0, 0x3000
	global_load_dword v0, v0, s[12:13] offset:1024 sc1
	s_add_u32 s18, s12, 0x3400
	s_addc_u32 s19, s13, 0
	s_waitcnt vmcnt(0)
	v_cmp_lt_u32_e32 vcc, v0, v1
	s_and_saveexec_b64 s[16:17], vcc
	s_cbranch_execz .LBB0_878
	s_mov_b32 s4, 1
	s_mov_b64 s[20:21], 0
	v_mov_b32_e32 v0, 0
	s_branch .LBB0_869

; __device__ __forceinline__ unsigned xb_ld(unsigned* p)              { return __hip_atomic_load(p, __ATOMIC_RELAXED, __HIP_MEMORY_SCOPE_AGENT); }
; __device__ __forceinline__ unsigned xb_add(unsigned* p, unsigned v) { return __hip_atomic_fetch_add(p, v, __ATOMIC_RELAXED, __HIP_MEMORY_SCOPE_AGENT); }
; #define XB_SPIN(cond, bar) do { unsigned _sp = 0; while (cond) { \
;     if ((++_sp & 255u) == 0u) { if (xb_ld(&(bar)[XB_TMO])) break; if (_sp > XB_SPIN_CAP) { atomicAdd(&(bar)[XB_TMO], 1u); break; } } } } while (0)
; __device__ __forceinline__ void xcd_barrier(unsigned* barw, volatile LAS unsigned* stw, const int wv) {
;     ...
;             const unsigned og = xb_add(&bar[XB_TOP], 1u);
;             const unsigned tg = og / nx;
;             if (og + 1u == (tg + 1u) * nx) xb_add(&bar[XB_TOPGEN], 1u);
;             else XB_SPIN(xb_ld(&bar[XB_TOPGEN]) == tg, bar);
.LBB0_882:
	s_or_b64 exec, exec, s[16:17]
	v_cvt_f32_u32_e32 v3, v0
	s_waitcnt vmcnt(0)
	v_readfirstlane_b32 s4, v2
	s_add_u32 s12, s12, 0x3400
	s_addc_u32 s13, s13, 0
	v_rcp_iflag_f32_e32 v3, v3
	v_add_u32_e32 v1, s4, v1
	s_mov_b64 s[16:17], 0
	v_mul_f32_e32 v2, 0x4f7ffffe, v3
	v_cvt_u32_f32_e32 v2, v2
	v_sub_u32_e32 v3, 0, v0
	v_mul_lo_u32 v3, v3, v2
	v_mul_hi_u32 v3, v2, v3
	v_add_u32_e32 v2, v2, v3
	v_mul_hi_u32 v2, v1, v2
	v_mul_lo_u32 v3, v2, v0
	v_sub_u32_e32 v3, v1, v3
	v_add_u32_e32 v4, 1, v2
	v_cmp_ge_u32_e32 vcc, v3, v0
	v_add_u32_e32 v1, 1, v1
	s_nop 0
	v_cndmask_b32_e32 v2, v2, v4, vcc
	v_sub_u32_e32 v4, v3, v0
	v_cndmask_b32_e32 v3, v3, v4, vcc
	v_add_u32_e32 v4, 1, v2
	v_cmp_ge_u32_e32 vcc, v3, v0
	s_nop 1
	v_cndmask_b32_e32 v2, v2, v4, vcc
	v_mul_lo_u32 v3, v0, v2
	v_add_u32_e32 v0, v3, v0
	v_mov_b32_e32 v17, v0
	v_cmp_ne_u32_e32 vcc, v1, v0
	v_mov_b64_e32 v[0:1], s[12:13]
	s_and_saveexec_b64 s[14:15], vcc
	s_cbranch_execz .LBB0_894
	v_mov_b32_e32 v0, 0
	global_load_dword v1, v0, s[12:13] sc1
	s_mov_b64 s[18:19], 0
	s_waitcnt vmcnt(0)
	v_cmp_lt_u32_e32 vcc, v1, v17
	s_and_saveexec_b64 s[16:17], vcc
	s_cbranch_execz .LBB0_893
	s_mov_b32 s4, 1
	s_branch .LBB0_886

; __device__ __forceinline__ unsigned xb_ld(unsigned* p)              { return __hip_atomic_load(p, __ATOMIC_RELAXED, __HIP_MEMORY_SCOPE_AGENT); }
; #define XB_SPIN(cond, bar) do { unsigned _sp = 0; while (cond) { \
;     if ((++_sp & 255u) == 0u) { if (xb_ld(&(bar)[XB_TMO])) break; if (_sp > XB_SPIN_CAP) { atomicAdd(&(bar)[XB_TMO], 1u); break; } } } } while (0)
; __device__ __forceinline__ void xcd_barrier(unsigned* barw, volatile LAS unsigned* stw, const int wv) {
;     ...
;             else XB_SPIN(xb_ld(&bar[XB_TOPGEN]) == tg, bar);
.LBB0_890:
	global_load_dword v1, v0, s[12:13] sc1
	s_add_i32 s4, s4, 1
	s_mov_b64 s[22:23], -1
	s_waitcnt vmcnt(0)
	v_cmp_ge_u32_e32 vcc, v1, v17
	s_orn2_b64 s[26:27], vcc, exec
	s_branch .LBB0_885

; __device__ __forceinline__ unsigned xb_ld(unsigned* p)              { return __hip_atomic_load(p, __ATOMIC_RELAXED, __HIP_MEMORY_SCOPE_AGENT); }
; __device__ __forceinline__ unsigned xb_add(unsigned* p, unsigned v) { return __hip_atomic_fetch_add(p, v, __ATOMIC_RELAXED, __HIP_MEMORY_SCOPE_AGENT); }
; #define XB_SPIN(cond, bar) do { unsigned _sp = 0; while (cond) { \
;     if ((++_sp & 255u) == 0u) { if (xb_ld(&(bar)[XB_TMO])) break; if (_sp > XB_SPIN_CAP) { atomicAdd(&(bar)[XB_TMO], 1u); break; } } } } while (0)
; __device__ __forceinline__ void xcd_barrier(unsigned* barw, volatile LAS unsigned* stw, const int wv) {
;     ...
;         const unsigned old = xb_add(&bar[XB_XSUB(b.x)], 1u);
;         const unsigned gen = old / nloc;
;         if (old + 1u == (gen + 1u) * nloc) {
;             __builtin_amdgcn_fence(__ATOMIC_RELEASE, "agent");
;             asm volatile("s_waitcnt vmcnt(0)" ::: "memory");
;             const unsigned og = xb_add(&bar[XB_TOP], 1u);
;             const unsigned tg = og / nx;
;             if (og + 1u == (tg + 1u) * nx) xb_add(&bar[XB_TOPGEN], 1u);
;             else XB_SPIN(xb_ld(&bar[XB_TOPGEN]) == tg, bar);
;             __builtin_amdgcn_fence(__ATOMIC_ACQUIRE, "agent");
;             xb_add(&bar[XB_XGEN(b.x)], 1u);
;             asm volatile("s_waitcnt vmcnt(0)" ::: "memory");
;         } else {
;             XB_SPIN(xb_ld(&bar[XB_XGEN(b.x)]) == gen, bar);
.LBB0_959:
	s_or_b64 exec, exec, s[10:11]
	v_cvt_f32_u32_e32 v4, v2
	s_waitcnt vmcnt(0)
	v_readfirstlane_b32 s8, v3
	v_sub_u32_e32 v3, 0, v2
	v_rcp_iflag_f32_e32 v4, v4
	v_add_u32_e32 v5, s8, v1
	v_mul_f32_e32 v4, 0x4f7ffffe, v4
	v_cvt_u32_f32_e32 v4, v4
	v_mul_lo_u32 v1, v3, v4
	v_mul_hi_u32 v1, v4, v1
	v_add_u32_e32 v1, v4, v1
	v_mul_hi_u32 v1, v5, v1
	v_mul_lo_u32 v3, v1, v2
	v_sub_u32_e32 v3, v5, v3
	v_add_u32_e32 v4, 1, v1
	v_cmp_ge_u32_e32 vcc, v3, v2
	s_nop 1
	v_cndmask_b32_e32 v1, v1, v4, vcc
	v_sub_u32_e32 v4, v3, v2
	v_cndmask_b32_e32 v3, v3, v4, vcc
	v_add_u32_e32 v4, 1, v1
	v_cmp_ge_u32_e32 vcc, v3, v2
	v_add_u32_e32 v3, 1, v5
	s_nop 0
	v_cndmask_b32_e32 v1, v1, v4, vcc
	v_mul_lo_u32 v4, v2, v1
	v_add_u32_e32 v2, v4, v2
	v_cmp_ne_u32_e32 vcc, v3, v2
	s_and_saveexec_b64 s[8:9], vcc
	s_xor_b64 s[8:9], exec, s[8:9]
	s_cbranch_execz .LBB0_973
	s_waitcnt lgkmcnt(0)
	v_mad_u32_u24 v1, v1, v0, v0
	v_mov_b32_e32 v0, 0x3000
	global_load_dword v0, v0, s[12:13] offset:1024 sc1
	s_add_u32 s14, s12, 0x3400
	s_addc_u32 s15, s13, 0
	s_waitcnt vmcnt(0)
	v_cmp_lt_u32_e32 vcc, v0, v1
	s_and_saveexec_b64 s[10:11], vcc
	s_cbranch_execz .LBB0_972
	s_mov_b32 s26, 1
	s_mov_b64 s[16:17], 0
	v_mov_b32_e32 v0, 0
	s_branch .LBB0_963

; __device__ __forceinline__ unsigned xb_ld(unsigned* p)              { return __hip_atomic_load(p, __ATOMIC_RELAXED, __HIP_MEMORY_SCOPE_AGENT); }
; #define XB_SPIN(cond, bar) do { unsigned _sp = 0; while (cond) { \
;     if ((++_sp & 255u) == 0u) { if (xb_ld(&(bar)[XB_TMO])) break; if (_sp > XB_SPIN_CAP) { atomicAdd(&(bar)[XB_TMO], 1u); break; } } } } while (0)
; __device__ __forceinline__ void xcd_barrier(unsigned* barw, volatile LAS unsigned* stw, const int wv) {
;     ...
;             XB_SPIN(xb_ld(&bar[XB_XGEN(b.x)]) == gen, bar);
.LBB0_967:
	global_load_dword v2, v0, s[14:15] sc1
	s_add_i32 s26, s26, 1
	s_mov_b64 s[22:23], -1
	s_waitcnt vmcnt(0)
	v_cmp_ge_u32_e32 vcc, v2, v1
	s_orn2_b64 s[20:21], vcc, exec
	s_branch .LBB0_962

; __device__ __forceinline__ unsigned xb_ld(unsigned* p)              { return __hip_atomic_load(p, __ATOMIC_RELAXED, __HIP_MEMORY_SCOPE_AGENT); }
; __device__ __forceinline__ unsigned xb_add(unsigned* p, unsigned v) { return __hip_atomic_fetch_add(p, v, __ATOMIC_RELAXED, __HIP_MEMORY_SCOPE_AGENT); }
; #define XB_SPIN(cond, bar) do { unsigned _sp = 0; while (cond) { \
;     if ((++_sp & 255u) == 0u) { if (xb_ld(&(bar)[XB_TMO])) break; if (_sp > XB_SPIN_CAP) { atomicAdd(&(bar)[XB_TMO], 1u); break; } } } } while (0)
; __device__ __forceinline__ void xcd_barrier(unsigned* barw, volatile LAS unsigned* stw, const int wv) {
;     ...
;             const unsigned og = xb_add(&bar[XB_TOP], 1u);
;             const unsigned tg = og / nx;
;             if (og + 1u == (tg + 1u) * nx) xb_add(&bar[XB_TOPGEN], 1u);
;             else XB_SPIN(xb_ld(&bar[XB_TOPGEN]) == tg, bar);
.LBB0_976:
	s_or_b64 exec, exec, s[10:11]
	v_cvt_f32_u32_e32 v3, v0
	s_waitcnt vmcnt(0)
	v_readfirstlane_b32 s10, v2
	s_add_u32 s8, s12, 0x3400
	s_addc_u32 s9, s13, 0
	v_rcp_iflag_f32_e32 v3, v3
	v_add_u32_e32 v1, s10, v1
	s_mov_b64 s[12:13], 0
	v_mul_f32_e32 v2, 0x4f7ffffe, v3
	v_cvt_u32_f32_e32 v2, v2
	v_sub_u32_e32 v3, 0, v0
	v_mul_lo_u32 v3, v3, v2
	v_mul_hi_u32 v3, v2, v3
	v_add_u32_e32 v2, v2, v3
	v_mul_hi_u32 v2, v1, v2
	v_mul_lo_u32 v3, v2, v0
	v_sub_u32_e32 v3, v1, v3
	v_add_u32_e32 v4, 1, v2
	v_cmp_ge_u32_e32 vcc, v3, v0
	v_add_u32_e32 v1, 1, v1
	s_nop 0
	v_cndmask_b32_e32 v2, v2, v4, vcc
	v_sub_u32_e32 v4, v3, v0
	v_cndmask_b32_e32 v3, v3, v4, vcc
	v_add_u32_e32 v4, 1, v2
	v_cmp_ge_u32_e32 vcc, v3, v0
	s_nop 1
	v_cndmask_b32_e32 v2, v2, v4, vcc
	v_mul_lo_u32 v3, v0, v2
	v_add_u32_e32 v0, v3, v0
	v_mov_b32_e32 v17, v0
	v_cmp_ne_u32_e32 vcc, v1, v0
	v_mov_b64_e32 v[0:1], s[8:9]
	s_and_saveexec_b64 s[10:11], vcc
	s_cbranch_execz .LBB0_988
	v_mov_b32_e32 v0, 0
	global_load_dword v1, v0, s[8:9] sc1
	s_mov_b64 s[14:15], 0
	s_waitcnt vmcnt(0)
	v_cmp_lt_u32_e32 vcc, v1, v17
	s_and_saveexec_b64 s[12:13], vcc
	s_cbranch_execz .LBB0_987
	s_mov_b32 s24, 1
	s_branch .LBB0_980

; __device__ __forceinline__ unsigned xb_ld(unsigned* p)              { return __hip_atomic_load(p, __ATOMIC_RELAXED, __HIP_MEMORY_SCOPE_AGENT); }
; #define XB_SPIN(cond, bar) do { unsigned _sp = 0; while (cond) { \
;     if ((++_sp & 255u) == 0u) { if (xb_ld(&(bar)[XB_TMO])) break; if (_sp > XB_SPIN_CAP) { atomicAdd(&(bar)[XB_TMO], 1u); break; } } } } while (0)
; __device__ __forceinline__ void xcd_barrier(unsigned* barw, volatile LAS unsigned* stw, const int wv) {
;     ...
;             else XB_SPIN(xb_ld(&bar[XB_TOPGEN]) == tg, bar);
.LBB0_984:
	global_load_dword v1, v0, s[8:9] sc1
	s_add_i32 s24, s24, 1
	s_mov_b64 s[18:19], -1
	s_waitcnt vmcnt(0)
	v_cmp_ge_u32_e32 vcc, v1, v17
	s_orn2_b64 s[22:23], vcc, exec
	s_branch .LBB0_979

; __device__ __forceinline__ unsigned xb_ld(unsigned* p)              { return __hip_atomic_load(p, __ATOMIC_RELAXED, __HIP_MEMORY_SCOPE_AGENT); }
; __device__ __forceinline__ unsigned xb_add(unsigned* p, unsigned v) { return __hip_atomic_fetch_add(p, v, __ATOMIC_RELAXED, __HIP_MEMORY_SCOPE_AGENT); }
; #define XB_SPIN(cond, bar) do { unsigned _sp = 0; while (cond) { \
;     if ((++_sp & 255u) == 0u) { if (xb_ld(&(bar)[XB_TMO])) break; if (_sp > XB_SPIN_CAP) { atomicAdd(&(bar)[XB_TMO], 1u); break; } } } } while (0)
; __device__ __forceinline__ void xcd_barrier(unsigned* barw, volatile LAS unsigned* stw, const int wv) {
;     ...
;         const unsigned old = xb_add(&bar[XB_XSUB(b.x)], 1u);
;         const unsigned gen = old / nloc;
;         if (old + 1u == (gen + 1u) * nloc) {
;             __builtin_amdgcn_fence(__ATOMIC_RELEASE, "agent");
;             asm volatile("s_waitcnt vmcnt(0)" ::: "memory");
;             const unsigned og = xb_add(&bar[XB_TOP], 1u);
;             const unsigned tg = og / nx;
;             if (og + 1u == (tg + 1u) * nx) xb_add(&bar[XB_TOPGEN], 1u);
;             else XB_SPIN(xb_ld(&bar[XB_TOPGEN]) == tg, bar);
;             __builtin_amdgcn_fence(__ATOMIC_ACQUIRE, "agent");
;             xb_add(&bar[XB_XGEN(b.x)], 1u);
;             asm volatile("s_waitcnt vmcnt(0)" ::: "memory");
;         } else {
;             XB_SPIN(xb_ld(&bar[XB_XGEN(b.x)]) == gen, bar);
.LBB0_1031:
	s_or_b64 exec, exec, s[10:11]
	v_cvt_f32_u32_e32 v4, v2
	s_waitcnt vmcnt(0)
	v_readfirstlane_b32 s6, v3
	v_sub_u32_e32 v3, 0, v2
	v_rcp_iflag_f32_e32 v4, v4
	v_add_u32_e32 v5, s6, v1
	v_mul_f32_e32 v4, 0x4f7ffffe, v4
	v_cvt_u32_f32_e32 v4, v4
	v_mul_lo_u32 v1, v3, v4
	v_mul_hi_u32 v1, v4, v1
	v_add_u32_e32 v1, v4, v1
	v_mul_hi_u32 v1, v5, v1
	v_mul_lo_u32 v3, v1, v2
	v_sub_u32_e32 v3, v5, v3
	v_add_u32_e32 v4, 1, v1
	v_cmp_ge_u32_e32 vcc, v3, v2
	s_nop 1
	v_cndmask_b32_e32 v1, v1, v4, vcc
	v_sub_u32_e32 v4, v3, v2
	v_cndmask_b32_e32 v3, v3, v4, vcc
	v_add_u32_e32 v4, 1, v1
	v_cmp_ge_u32_e32 vcc, v3, v2
	v_add_u32_e32 v3, 1, v5
	s_nop 0
	v_cndmask_b32_e32 v1, v1, v4, vcc
	v_mul_lo_u32 v4, v2, v1
	v_add_u32_e32 v2, v4, v2
	v_cmp_ne_u32_e32 vcc, v3, v2
	s_and_saveexec_b64 s[6:7], vcc
	s_xor_b64 s[6:7], exec, s[6:7]
	s_cbranch_execz .LBB0_1045
	s_waitcnt lgkmcnt(0)
	v_mad_u32_u24 v1, v1, v0, v0
	v_mov_b32_e32 v0, 0x3000
	global_load_dword v0, v0, s[8:9] offset:1024 sc1
	s_add_u32 s12, s8, 0x3400
	s_addc_u32 s13, s9, 0
	s_waitcnt vmcnt(0)
	v_cmp_lt_u32_e32 vcc, v0, v1
	s_and_saveexec_b64 s[10:11], vcc
	s_cbranch_execz .LBB0_1044
	s_mov_b32 s24, 1
	s_mov_b64 s[14:15], 0
	v_mov_b32_e32 v0, 0
	s_branch .LBB0_1035

; __device__ __forceinline__ unsigned xb_ld(unsigned* p)              { return __hip_atomic_load(p, __ATOMIC_RELAXED, __HIP_MEMORY_SCOPE_AGENT); }
; #define XB_SPIN(cond, bar) do { unsigned _sp = 0; while (cond) { \
;     if ((++_sp & 255u) == 0u) { if (xb_ld(&(bar)[XB_TMO])) break; if (_sp > XB_SPIN_CAP) { atomicAdd(&(bar)[XB_TMO], 1u); break; } } } } while (0)
; __device__ __forceinline__ void xcd_barrier(unsigned* barw, volatile LAS unsigned* stw, const int wv) {
;     ...
;             XB_SPIN(xb_ld(&bar[XB_XGEN(b.x)]) == gen, bar);
.LBB0_1039:
	global_load_dword v2, v0, s[12:13] sc1
	s_add_i32 s24, s24, 1
	s_mov_b64 s[20:21], -1
	s_waitcnt vmcnt(0)
	v_cmp_ge_u32_e32 vcc, v2, v1
	s_orn2_b64 s[18:19], vcc, exec
	s_branch .LBB0_1034

; __device__ __forceinline__ unsigned xb_ld(unsigned* p)              { return __hip_atomic_load(p, __ATOMIC_RELAXED, __HIP_MEMORY_SCOPE_AGENT); }
; __device__ __forceinline__ unsigned xb_add(unsigned* p, unsigned v) { return __hip_atomic_fetch_add(p, v, __ATOMIC_RELAXED, __HIP_MEMORY_SCOPE_AGENT); }
; #define XB_SPIN(cond, bar) do { unsigned _sp = 0; while (cond) { \
;     if ((++_sp & 255u) == 0u) { if (xb_ld(&(bar)[XB_TMO])) break; if (_sp > XB_SPIN_CAP) { atomicAdd(&(bar)[XB_TMO], 1u); break; } } } } while (0)
; __device__ __forceinline__ void xcd_barrier(unsigned* barw, volatile LAS unsigned* stw, const int wv) {
;     ...
;             const unsigned og = xb_add(&bar[XB_TOP], 1u);
;             const unsigned tg = og / nx;
;             if (og + 1u == (tg + 1u) * nx) xb_add(&bar[XB_TOPGEN], 1u);
;             else XB_SPIN(xb_ld(&bar[XB_TOPGEN]) == tg, bar);
.LBB0_1048:
	s_or_b64 exec, exec, s[10:11]
	v_cvt_f32_u32_e32 v3, v0
	s_add_u32 s6, s8, 0x3400
	s_waitcnt vmcnt(0)
	v_readfirstlane_b32 s8, v2
	s_addc_u32 s7, s9, 0
	v_rcp_iflag_f32_e32 v3, v3
	v_add_u32_e32 v1, s8, v1
	s_mov_b64 s[10:11], 0
	v_mul_f32_e32 v2, 0x4f7ffffe, v3
	v_cvt_u32_f32_e32 v2, v2
	v_sub_u32_e32 v3, 0, v0
	v_mul_lo_u32 v3, v3, v2
	v_mul_hi_u32 v3, v2, v3
	v_add_u32_e32 v2, v2, v3
	v_mul_hi_u32 v2, v1, v2
	v_mul_lo_u32 v3, v2, v0
	v_sub_u32_e32 v3, v1, v3
	v_add_u32_e32 v4, 1, v2
	v_cmp_ge_u32_e32 vcc, v3, v0
	v_add_u32_e32 v1, 1, v1
	s_nop 0
	v_cndmask_b32_e32 v2, v2, v4, vcc
	v_sub_u32_e32 v4, v3, v0
	v_cndmask_b32_e32 v3, v3, v4, vcc
	v_add_u32_e32 v4, 1, v2
	v_cmp_ge_u32_e32 vcc, v3, v0
	s_nop 1
	v_cndmask_b32_e32 v2, v2, v4, vcc
	v_mul_lo_u32 v3, v0, v2
	v_add_u32_e32 v0, v3, v0
	v_mov_b32_e32 v17, v0
	v_cmp_ne_u32_e32 vcc, v1, v0
	v_mov_b64_e32 v[0:1], s[6:7]
	s_and_saveexec_b64 s[8:9], vcc
	s_cbranch_execz .LBB0_1060
	v_mov_b32_e32 v0, 0
	global_load_dword v1, v0, s[6:7] sc1
	s_mov_b64 s[12:13], 0
	s_waitcnt vmcnt(0)
	v_cmp_lt_u32_e32 vcc, v1, v17
	s_and_saveexec_b64 s[10:11], vcc
	s_cbranch_execz .LBB0_1059
	s_mov_b32 s22, 1
	s_branch .LBB0_1052

; __device__ __forceinline__ unsigned xb_ld(unsigned* p)              { return __hip_atomic_load(p, __ATOMIC_RELAXED, __HIP_MEMORY_SCOPE_AGENT); }
; #define XB_SPIN(cond, bar) do { unsigned _sp = 0; while (cond) { \
;     if ((++_sp & 255u) == 0u) { if (xb_ld(&(bar)[XB_TMO])) break; if (_sp > XB_SPIN_CAP) { atomicAdd(&(bar)[XB_TMO], 1u); break; } } } } while (0)
; __device__ __forceinline__ void xcd_barrier(unsigned* barw, volatile LAS unsigned* stw, const int wv) {
;     ...
;             else XB_SPIN(xb_ld(&bar[XB_TOPGEN]) == tg, bar);
.LBB0_1056:
	global_load_dword v1, v0, s[6:7] sc1
	s_add_i32 s22, s22, 1
	s_mov_b64 s[16:17], -1
	s_waitcnt vmcnt(0)
	v_cmp_ge_u32_e32 vcc, v1, v17
	s_orn2_b64 s[20:21], vcc, exec
	s_branch .LBB0_1051

; __device__ __forceinline__ unsigned xb_ld(unsigned* p)              { return __hip_atomic_load(p, __ATOMIC_RELAXED, __HIP_MEMORY_SCOPE_AGENT); }
; __device__ __forceinline__ unsigned xb_add(unsigned* p, unsigned v) { return __hip_atomic_fetch_add(p, v, __ATOMIC_RELAXED, __HIP_MEMORY_SCOPE_AGENT); }
; #define XB_SPIN(cond, bar) do { unsigned _sp = 0; while (cond) { \
;     if ((++_sp & 255u) == 0u) { if (xb_ld(&(bar)[XB_TMO])) break; if (_sp > XB_SPIN_CAP) { atomicAdd(&(bar)[XB_TMO], 1u); break; } } } } while (0)
; __device__ __forceinline__ void xcd_barrier(unsigned* barw, volatile LAS unsigned* stw, const int wv) {
;     ...
;         const unsigned old = xb_add(&bar[XB_XSUB(b.x)], 1u);
;         const unsigned gen = old / nloc;
;         if (old + 1u == (gen + 1u) * nloc) {
;             __builtin_amdgcn_fence(__ATOMIC_RELEASE, "agent");
;             asm volatile("s_waitcnt vmcnt(0)" ::: "memory");
;             const unsigned og = xb_add(&bar[XB_TOP], 1u);
;             const unsigned tg = og / nx;
;             if (og + 1u == (tg + 1u) * nx) xb_add(&bar[XB_TOPGEN], 1u);
;             else XB_SPIN(xb_ld(&bar[XB_TOPGEN]) == tg, bar);
;             __builtin_amdgcn_fence(__ATOMIC_ACQUIRE, "agent");
;             xb_add(&bar[XB_XGEN(b.x)], 1u);
;             asm volatile("s_waitcnt vmcnt(0)" ::: "memory");
;         } else {
;             XB_SPIN(xb_ld(&bar[XB_XGEN(b.x)]) == gen, bar);
.LBB0_1101:
	s_or_b64 exec, exec, s[10:11]
	v_cvt_f32_u32_e32 v4, v2
	s_waitcnt vmcnt(0)
	v_readfirstlane_b32 s8, v3
	v_sub_u32_e32 v3, 0, v2
	v_rcp_iflag_f32_e32 v4, v4
	v_add_u32_e32 v5, s8, v1
	v_mul_f32_e32 v4, 0x4f7ffffe, v4
	v_cvt_u32_f32_e32 v4, v4
	v_mul_lo_u32 v1, v3, v4
	v_mul_hi_u32 v1, v4, v1
	v_add_u32_e32 v1, v4, v1
	v_mul_hi_u32 v1, v5, v1
	v_mul_lo_u32 v3, v1, v2
	v_sub_u32_e32 v3, v5, v3
	v_add_u32_e32 v4, 1, v1
	v_cmp_ge_u32_e32 vcc, v3, v2
	s_nop 1
	v_cndmask_b32_e32 v1, v1, v4, vcc
	v_sub_u32_e32 v4, v3, v2
	v_cndmask_b32_e32 v3, v3, v4, vcc
	v_add_u32_e32 v4, 1, v1
	v_cmp_ge_u32_e32 vcc, v3, v2
	v_add_u32_e32 v3, 1, v5
	s_nop 0
	v_cndmask_b32_e32 v1, v1, v4, vcc
	v_mul_lo_u32 v4, v2, v1
	v_add_u32_e32 v2, v4, v2
	v_cmp_ne_u32_e32 vcc, v3, v2
	s_and_saveexec_b64 s[8:9], vcc
	s_xor_b64 s[8:9], exec, s[8:9]
	s_cbranch_execz .LBB0_1115
	s_waitcnt lgkmcnt(0)
	v_mad_u32_u24 v1, v1, v0, v0
	v_mov_b32_e32 v0, 0x3000
	global_load_dword v0, v0, s[2:3] offset:1024 sc1
	s_add_u32 s12, s2, 0x3400
	s_addc_u32 s13, s3, 0
	s_waitcnt vmcnt(0)
	v_cmp_lt_u32_e32 vcc, v0, v1
	s_and_saveexec_b64 s[10:11], vcc
	s_cbranch_execz .LBB0_1114
	s_mov_b32 s24, 1
	s_mov_b64 s[14:15], 0
	v_mov_b32_e32 v0, 0
	s_branch .LBB0_1105

; __device__ __forceinline__ unsigned xb_ld(unsigned* p)              { return __hip_atomic_load(p, __ATOMIC_RELAXED, __HIP_MEMORY_SCOPE_AGENT); }
; __device__ __forceinline__ unsigned xb_add(unsigned* p, unsigned v) { return __hip_atomic_fetch_add(p, v, __ATOMIC_RELAXED, __HIP_MEMORY_SCOPE_AGENT); }
; #define XB_SPIN(cond, bar) do { unsigned _sp = 0; while (cond) { \
;     if ((++_sp & 255u) == 0u) { if (xb_ld(&(bar)[XB_TMO])) break; if (_sp > XB_SPIN_CAP) { atomicAdd(&(bar)[XB_TMO], 1u); break; } } } } while (0)
; __device__ __forceinline__ void xcd_barrier(unsigned* barw, volatile LAS unsigned* stw, const int wv) {
;     ...
;             const unsigned og = xb_add(&bar[XB_TOP], 1u);
;             const unsigned tg = og / nx;
;             if (og + 1u == (tg + 1u) * nx) xb_add(&bar[XB_TOPGEN], 1u);
;             else XB_SPIN(xb_ld(&bar[XB_TOPGEN]) == tg, bar);
.LBB0_1118:
	s_or_b64 exec, exec, s[10:11]
	v_cvt_f32_u32_e32 v3, v0
	s_waitcnt vmcnt(0)
	v_readfirstlane_b32 s8, v2
	s_add_u32 s2, s2, 0x3400
	s_addc_u32 s3, s3, 0
	v_rcp_iflag_f32_e32 v3, v3
	v_add_u32_e32 v1, s8, v1
	s_mov_b64 s[10:11], 0
	v_mul_f32_e32 v2, 0x4f7ffffe, v3
	v_cvt_u32_f32_e32 v2, v2
	v_sub_u32_e32 v3, 0, v0
	v_mul_lo_u32 v3, v3, v2
	v_mul_hi_u32 v3, v2, v3
	v_add_u32_e32 v2, v2, v3
	v_mul_hi_u32 v2, v1, v2
	v_mul_lo_u32 v3, v2, v0
	v_sub_u32_e32 v3, v1, v3
	v_add_u32_e32 v4, 1, v2
	v_cmp_ge_u32_e32 vcc, v3, v0
	v_add_u32_e32 v1, 1, v1
	s_nop 0
	v_cndmask_b32_e32 v2, v2, v4, vcc
	v_sub_u32_e32 v4, v3, v0
	v_cndmask_b32_e32 v3, v3, v4, vcc
	v_add_u32_e32 v4, 1, v2
	v_cmp_ge_u32_e32 vcc, v3, v0
	s_nop 1
	v_cndmask_b32_e32 v2, v2, v4, vcc
	v_mul_lo_u32 v3, v0, v2
	v_add_u32_e32 v0, v3, v0
	v_mov_b32_e32 v17, v0
	v_cmp_ne_u32_e32 vcc, v1, v0
	v_mov_b64_e32 v[0:1], s[2:3]
	s_and_saveexec_b64 s[8:9], vcc
	s_cbranch_execz .LBB0_1130
	v_mov_b32_e32 v0, 0
	global_load_dword v1, v0, s[2:3] sc1
	s_mov_b64 s[12:13], 0
	s_waitcnt vmcnt(0)
	v_cmp_lt_u32_e32 vcc, v1, v17
	s_and_saveexec_b64 s[10:11], vcc
	s_cbranch_execz .LBB0_1129
	s_mov_b32 s22, 1
	s_branch .LBB0_1122

; __device__ __forceinline__ unsigned xb_ld(unsigned* p)              { return __hip_atomic_load(p, __ATOMIC_RELAXED, __HIP_MEMORY_SCOPE_AGENT); }
; #define XB_SPIN(cond, bar) do { unsigned _sp = 0; while (cond) { \
;     if ((++_sp & 255u) == 0u) { if (xb_ld(&(bar)[XB_TMO])) break; if (_sp > XB_SPIN_CAP) { atomicAdd(&(bar)[XB_TMO], 1u); break; } } } } while (0)
; __device__ __forceinline__ void xcd_barrier(unsigned* barw, volatile LAS unsigned* stw, const int wv) {
;     ...
;             else XB_SPIN(xb_ld(&bar[XB_TOPGEN]) == tg, bar);
.LBB0_1126:
	global_load_dword v1, v0, s[2:3] sc1
	s_add_i32 s22, s22, 1
	s_mov_b64 s[16:17], -1
	s_waitcnt vmcnt(0)
	v_cmp_ge_u32_e32 vcc, v1, v17
	s_orn2_b64 s[20:21], vcc, exec
	s_branch .LBB0_1121
